# P4 qk GEMM loop: per-phase s_setprio flips removed (age arbitration), on top of v50
# baseline (speedup 1.0000x reference)
; #define PG8_STAGE(bufoff, gbase, voff) do { _Pragma("unroll") for (int _i = 0; _i < 2; ++_i) \
;         __builtin_amdgcn_global_load_lds((const unsigned*)((const char*)(gbase) + (voff)[_i]), (PG8_LAS unsigned*)(lds + (bufoff) + ldsw + _i * 8192), 16, 0, 0); } while (0)
; #define PG8_LDA(dst, b, h) do { _Pragma("unroll") for (int m = 0; m < 4; ++m) _Pragma("unroll") for (int k = 0; k < 2; ++k) dst[m][k] = *(const PG8_LAS bf16x8*)(lds + PG8_SA(b, h) + aoff + m * 2048 + k * 1024); } while (0)
; #define PG8_LDB(dst, b, h) do { _Pragma("unroll") for (int n = 0; n < 2; ++n) _Pragma("unroll") for (int k = 0; k < 2; ++k) dst[n][k] = *(const PG8_LAS bf16x8*)(lds + PG8_SB(b, h) + boff + n * 2048 + k * 1024); } while (0)
; #define PG8_MMA(ai, bj, At, Bt) do { __builtin_amdgcn_s_setprio(1); _Pragma("unroll") for (int m = 0; m < 4; ++m) _Pragma("unroll") for (int n = 0; n < 2; ++n) _Pragma("unroll") for (int k = 0; k < 2; ++k) \
;         acc[ai][bj][m][n] = __builtin_amdgcn_mfma_f32_16x16x32_bf16(Bt[n][k], At[m][k], acc[ai][bj][m][n], 0, 0, 0); __builtin_amdgcn_s_setprio(0); } while (0)
; #define PG8_WAIT_V(n) asm volatile("s_waitcnt vmcnt(" #n ")" ::: "memory")
; #define PG8_WAIT_L(n) asm volatile("s_waitcnt lgkmcnt(" #n ")" ::: "memory")
; #define PG8_BAR __builtin_amdgcn_s_barrier()
; #define PG8_SCHED __builtin_amdgcn_sched_barrier(0)
; template <class Epi>
; DI void gemm_phase(PG8_LAS unsigned char* lds, const Gemm g, const StaticOrder& S, const Epi& E) {
;     ...
;             PG8_LDB(B0, 0, 0); PG8_LDB(B1, 0, 1); PG8_SCHED; PG8_LDA(At, 0, 0); PG8_STAGE(PG8_SA(1, 1), a1 + hstepA, voffA);
;             PG8_WAIT_V(8); PG8_WAIT_L(0); PG8_BAR; PG8_MMA(0, 0, At, B0); PG8_MMA(0, 1, At, B1); PG8_BAR; PG8_SCHED;
;             PG8_LDA(At, 0, 1); PG8_STAGE(PG8_SB(0, 0), b2, voffB); PG8_STAGE(PG8_SB(0, 1), b2 + hstepB, voffB); PG8_STAGE(PG8_SA(0, 0), a2, voffA);
;             PG8_WAIT_V(8); PG8_WAIT_L(0); PG8_BAR; PG8_MMA(1, 0, At, B0); PG8_MMA(1, 1, At, B1); PG8_BAR; PG8_SCHED;
.LBB0_466:
	s_ashr_i32 s29, s28, 31
	s_lshl_b64 s[30:31], s[28:29], 19
	ds_read_b128 v[0:3], v149
	ds_read_b128 v[4:7], v149 offset:1024
	ds_read_b128 v[8:11], v149 offset:2048
	ds_read_b128 v[12:15], v149 offset:3072
	ds_read_b128 v[16:19], v150
	ds_read_b128 v[20:23], v150 offset:1024
	ds_read_b128 v[24:27], v150 offset:2048
	ds_read_b128 v[28:31], v150 offset:3072
	s_add_u32 s18, s94, s30
	s_addc_u32 s19, s95, s31
	s_ashr_i32 s27, s26, 31
	s_lshl_b64 s[30:31], s[26:27], 9
	s_add_u32 s30, s18, s30
	s_addc_u32 s31, s19, s31
	s_and_b64 s[34:35], s[0:1], exec
	s_cselect_b32 s45, s31, s39
	s_cselect_b32 s44, s30, s38
	s_lshl_b64 s[34:35], s[26:27], 17
	s_add_u32 s34, s3, s34
	s_addc_u32 s35, s25, s35
	v_mov_b32_e32 v140, v250
	s_and_b64 s[42:43], s[0:1], exec
	s_cselect_b32 s43, s35, s89
	s_cselect_b32 s42, s34, s88
	s_add_u32 s94, s38, 0x40080
	s_addc_u32 s95, s39, 0
	s_add_i32 vcc_lo, s37, 0xc000
	v_lshl_add_u64 v[64:65], s[94:95], 0, v[128:129]
	s_mov_b32 m0, vcc_lo
	s_add_i32 s27, s37, 0xe000
	ds_read_b128 v[32:35], v151
	ds_read_b128 v[36:39], v151 offset:1024
	ds_read_b128 v[40:43], v151 offset:2048
	ds_read_b128 v[44:47], v151 offset:3072
	ds_read_b128 v[48:51], v151 offset:4096
	ds_read_b128 v[52:55], v151 offset:5120
	ds_read_b128 v[56:59], v151 offset:6144
	ds_read_b128 v[60:63], v151 offset:7168
	global_load_lds_dwordx4 v[64:65], off
	v_lshl_add_u64 v[64:65], s[94:95], 0, v[132:133]
	s_mov_b32 m0, s27
	s_nop 0
	global_load_lds_dwordx4 v[64:65], off
	s_waitcnt vmcnt(8)
	s_waitcnt lgkmcnt(0)
	s_barrier
	s_waitcnt lgkmcnt(0)
	v_mfma_f32_16x16x32_bf16 v[64:67], v[0:3], v[32:35], 0
	v_mfma_f32_16x16x32_bf16 v[68:71], v[8:11], v[32:35], 0
	v_mfma_f32_16x16x32_bf16 v[72:75], v[0:3], v[40:43], 0
	v_mfma_f32_16x16x32_bf16 v[76:79], v[8:11], v[40:43], 0
	v_mfma_f32_16x16x32_bf16 v[80:83], v[0:3], v[48:51], 0
	v_mfma_f32_16x16x32_bf16 v[84:87], v[8:11], v[48:51], 0
	v_mfma_f32_16x16x32_bf16 v[88:91], v[0:3], v[56:59], 0
	v_mfma_f32_16x16x32_bf16 v[92:95], v[8:11], v[56:59], 0
	v_mfma_f32_16x16x32_bf16 v[64:67], v[4:7], v[36:39], v[64:67]
	v_mfma_f32_16x16x32_bf16 v[68:71], v[12:15], v[36:39], v[68:71]
	v_mfma_f32_16x16x32_bf16 v[72:75], v[4:7], v[44:47], v[72:75]
	v_mfma_f32_16x16x32_bf16 v[76:79], v[12:15], v[44:47], v[76:79]
	v_mfma_f32_16x16x32_bf16 v[80:83], v[4:7], v[52:55], v[80:83]
	v_mfma_f32_16x16x32_bf16 v[84:87], v[12:15], v[52:55], v[84:87]
	v_mfma_f32_16x16x32_bf16 v[88:91], v[4:7], v[60:63], v[88:91]
	v_mfma_f32_16x16x32_bf16 v[92:95], v[12:15], v[60:63], v[92:95]
	v_mfma_f32_16x16x32_bf16 v[96:99], v[16:19], v[32:35], 0
	v_mfma_f32_16x16x32_bf16 v[32:35], v[24:27], v[32:35], 0
	v_mfma_f32_16x16x32_bf16 v[96:99], v[20:23], v[36:39], v[96:99]
	v_mfma_f32_16x16x32_bf16 v[32:35], v[28:31], v[36:39], v[32:35]
	v_mfma_f32_16x16x32_bf16 v[36:39], v[16:19], v[40:43], 0
	v_mfma_f32_16x16x32_bf16 v[40:43], v[24:27], v[40:43], 0
	v_mfma_f32_16x16x32_bf16 v[36:39], v[20:23], v[44:47], v[36:39]
	v_mfma_f32_16x16x32_bf16 v[40:43], v[28:31], v[44:47], v[40:43]
	v_mfma_f32_16x16x32_bf16 v[44:47], v[16:19], v[48:51], 0
	v_mfma_f32_16x16x32_bf16 v[48:51], v[24:27], v[48:51], 0
	v_mfma_f32_16x16x32_bf16 v[44:47], v[20:23], v[52:55], v[44:47]
	v_mfma_f32_16x16x32_bf16 v[48:51], v[28:31], v[52:55], v[48:51]
	v_mfma_f32_16x16x32_bf16 v[52:55], v[16:19], v[56:59], 0
	v_mfma_f32_16x16x32_bf16 v[56:59], v[24:27], v[56:59], 0
	v_mfma_f32_16x16x32_bf16 v[52:55], v[20:23], v[60:63], v[52:55]
	v_mfma_f32_16x16x32_bf16 v[56:59], v[28:31], v[60:63], v[56:59]
	s_barrier
	s_add_i32 s96, s57, s46
	v_lshl_add_u64 v[180:181], s[88:89], 0, v[130:131]
	s_add_i32 s29, s96, 0x2000
	v_lshl_add_u64 v[142:143], v[180:181], 0, s[14:15]
	s_mov_b32 m0, s96
	v_lshl_add_u64 v[216:217], s[88:89], 0, v[134:135]
	s_add_u32 s18, s88, 0x10100
	ds_read_b128 v[60:63], v151 offset:16384
	ds_read_b128 v[100:103], v151 offset:17408
	ds_read_b128 v[104:107], v151 offset:18432
	ds_read_b128 v[108:111], v151 offset:19456
	ds_read_b128 v[112:115], v151 offset:20480
	ds_read_b128 v[116:119], v151 offset:21504
	ds_read_b128 v[120:123], v151 offset:22528
	ds_read_b128 v[124:127], v151 offset:23552
	global_load_lds_dwordx4 v[142:143], off
	v_lshl_add_u64 v[142:143], v[216:217], 0, s[14:15]
	s_mov_b32 m0, s29
	s_addc_u32 s19, s89, 0
	s_add_i32 s94, s86, s46
	global_load_lds_dwordx4 v[142:143], off
	v_lshl_add_u64 v[142:143], s[18:19], 0, v[130:131]
	s_mov_b32 m0, s94
	s_add_i32 s95, s94, 0x2000
	global_load_lds_dwordx4 v[142:143], off
	v_lshl_add_u64 v[142:143], s[18:19], 0, v[134:135]
	s_mov_b32 m0, s95
	v_lshl_add_u64 v[218:219], s[38:39], 0, v[128:129]
	global_load_lds_dwordx4 v[142:143], off
	v_lshl_add_u64 v[142:143], v[218:219], 0, s[14:15]
	s_mov_b32 m0, s37
	v_lshl_add_u64 v[220:221], s[38:39], 0, v[132:133]
	global_load_lds_dwordx4 v[142:143], off
	v_lshl_add_u64 v[142:143], v[220:221], 0, s[14:15]
	s_mov_b32 m0, s47
	s_nop 0
	global_load_lds_dwordx4 v[142:143], off
	s_waitcnt vmcnt(8)
	s_waitcnt lgkmcnt(0)
	s_barrier
; #define PG8_STAGE(bufoff, gbase, voff) do { _Pragma("unroll") for (int _i = 0; _i < 2; ++_i) \
;         __builtin_amdgcn_global_load_lds((const unsigned*)((const char*)(gbase) + (voff)[_i]), (PG8_LAS unsigned*)(lds + (bufoff) + ldsw + _i * 8192), 16, 0, 0); } while (0)
; #define PG8_LDA(dst, b, h) do { _Pragma("unroll") for (int m = 0; m < 4; ++m) _Pragma("unroll") for (int k = 0; k < 2; ++k) dst[m][k] = *(const PG8_LAS bf16x8*)(lds + PG8_SA(b, h) + aoff + m * 2048 + k * 1024); } while (0)
; #define PG8_LDB(dst, b, h) do { _Pragma("unroll") for (int n = 0; n < 2; ++n) _Pragma("unroll") for (int k = 0; k < 2; ++k) dst[n][k] = *(const PG8_LAS bf16x8*)(lds + PG8_SB(b, h) + boff + n * 2048 + k * 1024); } while (0)
; #define PG8_MMA(ai, bj, At, Bt) do { __builtin_amdgcn_s_setprio(1); _Pragma("unroll") for (int m = 0; m < 4; ++m) _Pragma("unroll") for (int n = 0; n < 2; ++n) _Pragma("unroll") for (int k = 0; k < 2; ++k) \
;         acc[ai][bj][m][n] = __builtin_amdgcn_mfma_f32_16x16x32_bf16(Bt[n][k], At[m][k], acc[ai][bj][m][n], 0, 0, 0); __builtin_amdgcn_s_setprio(0); } while (0)
; #define PG8_WAIT_V(n) asm volatile("s_waitcnt vmcnt(" #n ")" ::: "memory")
; #define PG8_WAIT_L(n) asm volatile("s_waitcnt lgkmcnt(" #n ")" ::: "memory")
; #define PG8_BAR __builtin_amdgcn_s_barrier()
; #define PG8_SCHED __builtin_amdgcn_sched_barrier(0)
; template <class Epi>
; DI void gemm_phase(PG8_LAS unsigned char* lds, const Gemm g, const StaticOrder& S, const Epi& E) {
;     ...
;             PG8_WAIT_V(8); PG8_WAIT_L(0); PG8_BAR; PG8_MMA(1, 0, At, B0); PG8_MMA(1, 1, At, B1); PG8_BAR; PG8_SCHED;
;             PG8_LDB(B0, 1, 0); PG8_LDB(B1, 1, 1); PG8_SCHED; PG8_LDA(At, 1, 0); PG8_STAGE(PG8_SA(0, 1), a2 + hstepA, voffA);
;             PG8_WAIT_V(8); PG8_WAIT_L(0); PG8_BAR; PG8_MMA(0, 0, At, B0); PG8_MMA(0, 1, At, B1); PG8_BAR; PG8_SCHED;
	s_waitcnt lgkmcnt(0)
	v_mfma_f32_16x16x32_bf16 v[142:145], v[0:3], v[60:63], 0
	v_mfma_f32_16x16x32_bf16 v[156:159], v[0:3], v[104:107], 0
	v_mfma_f32_16x16x32_bf16 v[164:167], v[0:3], v[112:115], 0
	v_mfma_f32_16x16x32_bf16 v[0:3], v[0:3], v[120:123], 0
	v_mfma_f32_16x16x32_bf16 v[142:145], v[4:7], v[100:103], v[142:145]
	v_mfma_f32_16x16x32_bf16 v[156:159], v[4:7], v[108:111], v[156:159]
	v_mfma_f32_16x16x32_bf16 v[164:167], v[4:7], v[116:119], v[164:167]
	v_mfma_f32_16x16x32_bf16 v[0:3], v[4:7], v[124:127], v[0:3]
	v_mfma_f32_16x16x32_bf16 v[4:7], v[8:11], v[120:123], 0
	v_mfma_f32_16x16x32_bf16 v[152:155], v[8:11], v[60:63], 0
	v_mfma_f32_16x16x32_bf16 v[160:163], v[8:11], v[104:107], 0
	v_mfma_f32_16x16x32_bf16 v[168:171], v[8:11], v[112:115], 0
	v_mfma_f32_16x16x32_bf16 v[4:7], v[12:15], v[124:127], v[4:7]
	v_mfma_f32_16x16x32_bf16 v[152:155], v[12:15], v[100:103], v[152:155]
	v_mfma_f32_16x16x32_bf16 v[160:163], v[12:15], v[108:111], v[160:163]
	v_mfma_f32_16x16x32_bf16 v[168:171], v[12:15], v[116:119], v[168:171]
	v_mfma_f32_16x16x32_bf16 v[8:11], v[16:19], v[60:63], 0
	v_mfma_f32_16x16x32_bf16 v[12:15], v[24:27], v[60:63], 0
	v_mfma_f32_16x16x32_bf16 v[8:11], v[20:23], v[100:103], v[8:11]
	v_mfma_f32_16x16x32_bf16 v[12:15], v[28:31], v[100:103], v[12:15]
	v_mfma_f32_16x16x32_bf16 v[60:63], v[16:19], v[104:107], 0
	v_mfma_f32_16x16x32_bf16 v[100:103], v[24:27], v[104:107], 0
	v_mfma_f32_16x16x32_bf16 v[104:107], v[16:19], v[112:115], 0
	v_mfma_f32_16x16x32_bf16 v[16:19], v[16:19], v[120:123], 0
	v_mfma_f32_16x16x32_bf16 v[60:63], v[20:23], v[108:111], v[60:63]
	v_mfma_f32_16x16x32_bf16 v[100:103], v[28:31], v[108:111], v[100:103]
	v_mfma_f32_16x16x32_bf16 v[104:107], v[20:23], v[116:119], v[104:107]
	v_mfma_f32_16x16x32_bf16 v[108:111], v[24:27], v[112:115], 0
	v_mfma_f32_16x16x32_bf16 v[16:19], v[20:23], v[124:127], v[16:19]
	v_mfma_f32_16x16x32_bf16 v[20:23], v[24:27], v[120:123], 0
	v_mfma_f32_16x16x32_bf16 v[108:111], v[28:31], v[116:119], v[108:111]
	v_mfma_f32_16x16x32_bf16 v[20:23], v[28:31], v[124:127], v[20:23]
	s_barrier
	s_add_i32 vcc_hi, 16, 0x18000
	s_add_i32 s40, 16, 0x1c000
	v_add_u32_e32 v136, vcc_hi, v148
	v_add_u32_e32 v238, s40, v148
	ds_read_b128 v[24:27], v136
	ds_read_b128 v[28:31], v136 offset:1024
	ds_read_b128 v[112:115], v136 offset:2048
	ds_read_b128 v[116:119], v136 offset:3072
	ds_read_b128 v[120:123], v238
	ds_read_b128 v[124:127], v238 offset:1024
	ds_read_b128 v[172:175], v238 offset:2048
	ds_read_b128 v[176:179], v238 offset:3072
	s_add_u32 s18, s38, 0x40100
	s_addc_u32 s19, s39, 0
	s_mov_b32 m0, s48
	v_lshl_add_u64 v[222:223], s[18:19], 0, v[128:129]
	ds_read_b128 v[184:187], v151 offset:32768
	ds_read_b128 v[188:191], v151 offset:33792
	ds_read_b128 v[192:195], v151 offset:34816
	ds_read_b128 v[196:199], v151 offset:35840
	ds_read_b128 v[200:203], v151 offset:36864
	ds_read_b128 v[204:207], v151 offset:37888
	ds_read_b128 v[208:211], v151 offset:38912
	ds_read_b128 v[212:215], v151 offset:39936
	global_load_lds_dwordx4 v[222:223], off
	v_lshl_add_u64 v[222:223], s[18:19], 0, v[132:133]
	s_mov_b32 m0, s49
	s_nop 0
	global_load_lds_dwordx4 v[222:223], off
	s_waitcnt vmcnt(8)
	s_waitcnt lgkmcnt(0)
	s_barrier
	s_waitcnt lgkmcnt(0)
	v_mfma_f32_16x16x32_bf16 v[64:67], v[24:27], v[184:187], v[64:67]
	v_mfma_f32_16x16x32_bf16 v[68:71], v[112:115], v[184:187], v[68:71]
	v_mfma_f32_16x16x32_bf16 v[72:75], v[24:27], v[192:195], v[72:75]
	v_mfma_f32_16x16x32_bf16 v[76:79], v[112:115], v[192:195], v[76:79]
	v_mfma_f32_16x16x32_bf16 v[80:83], v[24:27], v[200:203], v[80:83]
	v_mfma_f32_16x16x32_bf16 v[84:87], v[112:115], v[200:203], v[84:87]
	v_mfma_f32_16x16x32_bf16 v[88:91], v[24:27], v[208:211], v[88:91]
	v_mfma_f32_16x16x32_bf16 v[92:95], v[112:115], v[208:211], v[92:95]
	v_mfma_f32_16x16x32_bf16 v[64:67], v[28:31], v[188:191], v[64:67]
	v_mfma_f32_16x16x32_bf16 v[68:71], v[116:119], v[188:191], v[68:71]
	v_mfma_f32_16x16x32_bf16 v[72:75], v[28:31], v[196:199], v[72:75]
	v_mfma_f32_16x16x32_bf16 v[76:79], v[116:119], v[196:199], v[76:79]
	v_mfma_f32_16x16x32_bf16 v[80:83], v[28:31], v[204:207], v[80:83]
	v_mfma_f32_16x16x32_bf16 v[84:87], v[116:119], v[204:207], v[84:87]
	v_mfma_f32_16x16x32_bf16 v[88:91], v[28:31], v[212:215], v[88:91]
	v_mfma_f32_16x16x32_bf16 v[92:95], v[116:119], v[212:215], v[92:95]
	v_mfma_f32_16x16x32_bf16 v[96:99], v[120:123], v[184:187], v[96:99]
	v_mfma_f32_16x16x32_bf16 v[32:35], v[172:175], v[184:187], v[32:35]
	v_mfma_f32_16x16x32_bf16 v[36:39], v[120:123], v[192:195], v[36:39]
	v_mfma_f32_16x16x32_bf16 v[40:43], v[172:175], v[192:195], v[40:43]
	v_mfma_f32_16x16x32_bf16 v[44:47], v[120:123], v[200:203], v[44:47]
	v_mfma_f32_16x16x32_bf16 v[48:51], v[172:175], v[200:203], v[48:51]
	v_mfma_f32_16x16x32_bf16 v[52:55], v[120:123], v[208:211], v[52:55]
	v_mfma_f32_16x16x32_bf16 v[56:59], v[172:175], v[208:211], v[56:59]
	v_mfma_f32_16x16x32_bf16 v[96:99], v[124:127], v[188:191], v[96:99]
	v_mfma_f32_16x16x32_bf16 v[32:35], v[176:179], v[188:191], v[32:35]
	v_mfma_f32_16x16x32_bf16 v[36:39], v[124:127], v[196:199], v[36:39]
	v_mfma_f32_16x16x32_bf16 v[40:43], v[176:179], v[196:199], v[40:43]
	v_mfma_f32_16x16x32_bf16 v[44:47], v[124:127], v[204:207], v[44:47]
	v_mfma_f32_16x16x32_bf16 v[48:51], v[176:179], v[204:207], v[48:51]
	v_mfma_f32_16x16x32_bf16 v[52:55], v[124:127], v[212:215], v[52:55]
	v_mfma_f32_16x16x32_bf16 v[56:59], v[176:179], v[212:215], v[56:59]
	s_barrier
; #define PG8_STAGE(bufoff, gbase, voff) do { _Pragma("unroll") for (int _i = 0; _i < 2; ++_i) \
;         __builtin_amdgcn_global_load_lds((const unsigned*)((const char*)(gbase) + (voff)[_i]), (PG8_LAS unsigned*)(lds + (bufoff) + ldsw + _i * 8192), 16, 0, 0); } while (0)
; #define PG8_LDA(dst, b, h) do { _Pragma("unroll") for (int m = 0; m < 4; ++m) _Pragma("unroll") for (int k = 0; k < 2; ++k) dst[m][k] = *(const PG8_LAS bf16x8*)(lds + PG8_SA(b, h) + aoff + m * 2048 + k * 1024); } while (0)
; #define PG8_LDB(dst, b, h) do { _Pragma("unroll") for (int n = 0; n < 2; ++n) _Pragma("unroll") for (int k = 0; k < 2; ++k) dst[n][k] = *(const PG8_LAS bf16x8*)(lds + PG8_SB(b, h) + boff + n * 2048 + k * 1024); } while (0)
; #define PG8_MMA(ai, bj, At, Bt) do { __builtin_amdgcn_s_setprio(1); _Pragma("unroll") for (int m = 0; m < 4; ++m) _Pragma("unroll") for (int n = 0; n < 2; ++n) _Pragma("unroll") for (int k = 0; k < 2; ++k) \
;         acc[ai][bj][m][n] = __builtin_amdgcn_mfma_f32_16x16x32_bf16(Bt[n][k], At[m][k], acc[ai][bj][m][n], 0, 0, 0); __builtin_amdgcn_s_setprio(0); } while (0)
; #define PG8_WAIT_V(n) asm volatile("s_waitcnt vmcnt(" #n ")" ::: "memory")
; #define PG8_WAIT_L(n) asm volatile("s_waitcnt lgkmcnt(" #n ")" ::: "memory")
; #define PG8_BAR __builtin_amdgcn_s_barrier()
; #define PG8_SCHED __builtin_amdgcn_sched_barrier(0)
; template <class Epi>
; DI void gemm_phase(PG8_LAS unsigned char* lds, const Gemm g, const StaticOrder& S, const Epi& E) {
;     ...
;             PG8_LDB(B0, 0, 0); PG8_LDB(B1, 0, 1); PG8_SCHED; PG8_LDA(At, 0, 0); PG8_STAGE(PG8_SA(1, 1), a1 + hstepA, voffA);
;             PG8_WAIT_V(8); PG8_WAIT_L(0); PG8_BAR; PG8_MMA(0, 0, At, B0); PG8_MMA(0, 1, At, B1); PG8_BAR; PG8_SCHED;
;     ...
;             PG8_LDA(At, 1, 1); PG8_STAGE(PG8_SB(1, 0), b3, voffB); PG8_STAGE(PG8_SB(1, 1), b3 + hstepB, voffB); PG8_STAGE(PG8_SA(1, 0), a3, voffA);
;             PG8_WAIT_V(8); PG8_WAIT_L(0); PG8_BAR; PG8_MMA(1, 0, At, B0); PG8_MMA(1, 1, At, B1); PG8_BAR; PG8_SCHED;
	s_add_i32 vcc_hi, vcc_hi, s46
	s_add_i32 s97, vcc_hi, 0x2000
	v_lshl_add_u64 v[180:181], v[180:181], 0, s[16:17]
	s_mov_b32 m0, vcc_hi
	s_add_u32 s18, s88, 0x10180
	ds_read_b128 v[184:187], v151 offset:49152
	ds_read_b128 v[188:191], v151 offset:50176
	ds_read_b128 v[192:195], v151 offset:51200
	ds_read_b128 v[196:199], v151 offset:52224
	ds_read_b128 v[200:203], v151 offset:53248
	ds_read_b128 v[204:207], v151 offset:54272
	ds_read_b128 v[208:211], v151 offset:55296
	ds_read_b128 v[212:215], v151 offset:56320
	global_load_lds_dwordx4 v[180:181], off
	v_lshl_add_u64 v[180:181], v[216:217], 0, s[16:17]
	s_mov_b32 m0, s97
	s_addc_u32 s19, s89, 0
	s_add_i32 s40, s40, s46
	global_load_lds_dwordx4 v[180:181], off
	v_lshl_add_u64 v[180:181], s[18:19], 0, v[130:131]
	s_mov_b32 m0, s40
	s_add_i32 s41, s40, 0x2000
	global_load_lds_dwordx4 v[180:181], off
	v_lshl_add_u64 v[180:181], s[18:19], 0, v[134:135]
	s_mov_b32 m0, s41
	s_nop 0
	global_load_lds_dwordx4 v[180:181], off
	v_lshl_add_u64 v[180:181], v[218:219], 0, s[16:17]
	s_mov_b32 m0, s53
	s_nop 0
	global_load_lds_dwordx4 v[180:181], off
	v_lshl_add_u64 v[180:181], v[220:221], 0, s[16:17]
	s_mov_b32 m0, s55
	s_nop 0
	global_load_lds_dwordx4 v[180:181], off
	s_waitcnt vmcnt(8)
	s_waitcnt lgkmcnt(0)
	s_barrier
	s_waitcnt lgkmcnt(0)
	v_mfma_f32_16x16x32_bf16 v[0:3], v[24:27], v[208:211], v[0:3]
	v_mfma_f32_16x16x32_bf16 v[4:7], v[112:115], v[208:211], v[4:7]
	v_mfma_f32_16x16x32_bf16 v[142:145], v[24:27], v[184:187], v[142:145]
	v_mfma_f32_16x16x32_bf16 v[152:155], v[112:115], v[184:187], v[152:155]
	v_mfma_f32_16x16x32_bf16 v[156:159], v[24:27], v[192:195], v[156:159]
	v_mfma_f32_16x16x32_bf16 v[160:163], v[112:115], v[192:195], v[160:163]
	v_mfma_f32_16x16x32_bf16 v[164:167], v[24:27], v[200:203], v[164:167]
	v_mfma_f32_16x16x32_bf16 v[168:171], v[112:115], v[200:203], v[168:171]
	v_mfma_f32_16x16x32_bf16 v[0:3], v[28:31], v[212:215], v[0:3]
	v_mfma_f32_16x16x32_bf16 v[4:7], v[116:119], v[212:215], v[4:7]
	v_mfma_f32_16x16x32_bf16 v[142:145], v[28:31], v[188:191], v[142:145]
	v_mfma_f32_16x16x32_bf16 v[152:155], v[116:119], v[188:191], v[152:155]
	v_mfma_f32_16x16x32_bf16 v[156:159], v[28:31], v[196:199], v[156:159]
	v_mfma_f32_16x16x32_bf16 v[160:163], v[116:119], v[196:199], v[160:163]
	v_mfma_f32_16x16x32_bf16 v[164:167], v[28:31], v[204:207], v[164:167]
	v_mfma_f32_16x16x32_bf16 v[168:171], v[116:119], v[204:207], v[168:171]
	v_mfma_f32_16x16x32_bf16 v[8:11], v[120:123], v[184:187], v[8:11]
	v_mfma_f32_16x16x32_bf16 v[12:15], v[172:175], v[184:187], v[12:15]
	v_mfma_f32_16x16x32_bf16 v[24:27], v[120:123], v[192:195], v[60:63]
	v_mfma_f32_16x16x32_bf16 v[28:31], v[172:175], v[192:195], v[100:103]
	v_mfma_f32_16x16x32_bf16 v[60:63], v[120:123], v[200:203], v[104:107]
	v_mfma_f32_16x16x32_bf16 v[100:103], v[172:175], v[200:203], v[108:111]
	v_mfma_f32_16x16x32_bf16 v[16:19], v[120:123], v[208:211], v[16:19]
	v_mfma_f32_16x16x32_bf16 v[20:23], v[172:175], v[208:211], v[20:23]
	v_mfma_f32_16x16x32_bf16 v[8:11], v[124:127], v[188:191], v[8:11]
	v_mfma_f32_16x16x32_bf16 v[12:15], v[176:179], v[188:191], v[12:15]
	v_mfma_f32_16x16x32_bf16 v[24:27], v[124:127], v[196:199], v[24:27]
	v_mfma_f32_16x16x32_bf16 v[28:31], v[176:179], v[196:199], v[28:31]
	v_mfma_f32_16x16x32_bf16 v[60:63], v[124:127], v[204:207], v[60:63]
	v_mfma_f32_16x16x32_bf16 v[100:103], v[176:179], v[204:207], v[100:103]
	v_mfma_f32_16x16x32_bf16 v[16:19], v[124:127], v[212:215], v[16:19]
	v_mfma_f32_16x16x32_bf16 v[20:23], v[176:179], v[212:215], v[20:23]
	s_barrier
	ds_read_b128 v[104:107], v149
	ds_read_b128 v[108:111], v149 offset:1024
	ds_read_b128 v[112:115], v149 offset:2048
	ds_read_b128 v[116:119], v149 offset:3072
	ds_read_b128 v[120:123], v150
	ds_read_b128 v[124:127], v150 offset:1024
	ds_read_b128 v[172:175], v150 offset:2048
	ds_read_b128 v[176:179], v150 offset:3072
	s_add_u32 s18, s38, 0x40180
	s_addc_u32 s19, s39, 0
	s_mov_b32 m0, vcc_lo
	v_lshl_add_u64 v[180:181], s[18:19], 0, v[128:129]
	ds_read_b128 v[184:187], v151
	ds_read_b128 v[188:191], v151 offset:1024
	ds_read_b128 v[192:195], v151 offset:2048
	ds_read_b128 v[196:199], v151 offset:3072
	ds_read_b128 v[200:203], v151 offset:4096
	ds_read_b128 v[204:207], v151 offset:5120
	ds_read_b128 v[208:211], v151 offset:6144
	ds_read_b128 v[212:215], v151 offset:7168
	global_load_lds_dwordx4 v[180:181], off
	v_lshl_add_u64 v[180:181], s[18:19], 0, v[132:133]
	s_mov_b32 m0, s27
	s_nop 0
	global_load_lds_dwordx4 v[180:181], off
	s_waitcnt vmcnt(8)
	s_waitcnt lgkmcnt(0)
	s_barrier
; #define PG8_STAGE(bufoff, gbase, voff) do { _Pragma("unroll") for (int _i = 0; _i < 2; ++_i) \
;         __builtin_amdgcn_global_load_lds((const unsigned*)((const char*)(gbase) + (voff)[_i]), (PG8_LAS unsigned*)(lds + (bufoff) + ldsw + _i * 8192), 16, 0, 0); } while (0)
; #define PG8_LDA(dst, b, h) do { _Pragma("unroll") for (int m = 0; m < 4; ++m) _Pragma("unroll") for (int k = 0; k < 2; ++k) dst[m][k] = *(const PG8_LAS bf16x8*)(lds + PG8_SA(b, h) + aoff + m * 2048 + k * 1024); } while (0)
; #define PG8_MMA(ai, bj, At, Bt) do { __builtin_amdgcn_s_setprio(1); _Pragma("unroll") for (int m = 0; m < 4; ++m) _Pragma("unroll") for (int n = 0; n < 2; ++n) _Pragma("unroll") for (int k = 0; k < 2; ++k) \
;         acc[ai][bj][m][n] = __builtin_amdgcn_mfma_f32_16x16x32_bf16(Bt[n][k], At[m][k], acc[ai][bj][m][n], 0, 0, 0); __builtin_amdgcn_s_setprio(0); } while (0)
; #define PG8_WAIT_V(n) asm volatile("s_waitcnt vmcnt(" #n ")" ::: "memory")
; #define PG8_WAIT_L(n) asm volatile("s_waitcnt lgkmcnt(" #n ")" ::: "memory")
; #define PG8_BAR __builtin_amdgcn_s_barrier()
; #define PG8_SCHED __builtin_amdgcn_sched_barrier(0)
; template <class Epi>
; DI void gemm_phase(PG8_LAS unsigned char* lds, const Gemm g, const StaticOrder& S, const Epi& E) {
;     ...
;             PG8_WAIT_V(8); PG8_WAIT_L(0); PG8_BAR; PG8_MMA(0, 0, At, B0); PG8_MMA(0, 1, At, B1); PG8_BAR; PG8_SCHED;
;             PG8_LDA(At, 0, 1); PG8_STAGE(PG8_SB(0, 0), b2, voffB); PG8_STAGE(PG8_SB(0, 1), b2 + hstepB, voffB); PG8_STAGE(PG8_SA(0, 0), a2, voffA);
;             PG8_WAIT_V(8); PG8_WAIT_L(0); PG8_BAR; PG8_MMA(1, 0, At, B0); PG8_MMA(1, 1, At, B1); PG8_BAR; PG8_SCHED;
	s_waitcnt lgkmcnt(0)
	v_mfma_f32_16x16x32_bf16 v[64:67], v[104:107], v[184:187], v[64:67]
	v_mfma_f32_16x16x32_bf16 v[68:71], v[112:115], v[184:187], v[68:71]
	v_mfma_f32_16x16x32_bf16 v[72:75], v[104:107], v[192:195], v[72:75]
	v_mfma_f32_16x16x32_bf16 v[76:79], v[112:115], v[192:195], v[76:79]
	v_mfma_f32_16x16x32_bf16 v[80:83], v[104:107], v[200:203], v[80:83]
	v_mfma_f32_16x16x32_bf16 v[84:87], v[112:115], v[200:203], v[84:87]
	v_mfma_f32_16x16x32_bf16 v[88:91], v[104:107], v[208:211], v[88:91]
	v_mfma_f32_16x16x32_bf16 v[64:67], v[108:111], v[188:191], v[64:67]
	v_mfma_f32_16x16x32_bf16 v[68:71], v[116:119], v[188:191], v[68:71]
	v_mfma_f32_16x16x32_bf16 v[72:75], v[108:111], v[196:199], v[72:75]
	v_mfma_f32_16x16x32_bf16 v[76:79], v[116:119], v[196:199], v[76:79]
	v_mfma_f32_16x16x32_bf16 v[80:83], v[108:111], v[204:207], v[80:83]
	v_mfma_f32_16x16x32_bf16 v[84:87], v[116:119], v[204:207], v[84:87]
	v_mfma_f32_16x16x32_bf16 v[216:219], v[108:111], v[212:215], v[88:91]
	v_mfma_f32_16x16x32_bf16 v[88:91], v[112:115], v[208:211], v[92:95]
	v_mfma_f32_16x16x32_bf16 v[220:223], v[116:119], v[212:215], v[88:91]
	v_mfma_f32_16x16x32_bf16 v[48:51], v[172:175], v[200:203], v[48:51]
	v_mfma_f32_16x16x32_bf16 v[88:91], v[120:123], v[184:187], v[96:99]
	v_mfma_f32_16x16x32_bf16 v[32:35], v[172:175], v[184:187], v[32:35]
	v_mfma_f32_16x16x32_bf16 v[36:39], v[120:123], v[192:195], v[36:39]
	v_mfma_f32_16x16x32_bf16 v[40:43], v[172:175], v[192:195], v[40:43]
	v_mfma_f32_16x16x32_bf16 v[44:47], v[120:123], v[200:203], v[44:47]
	v_mfma_f32_16x16x32_bf16 v[184:187], v[176:179], v[204:207], v[48:51]
	v_mfma_f32_16x16x32_bf16 v[48:51], v[120:123], v[208:211], v[52:55]
	v_mfma_f32_16x16x32_bf16 v[96:99], v[124:127], v[188:191], v[88:91]
	v_mfma_f32_16x16x32_bf16 v[32:35], v[176:179], v[188:191], v[32:35]
	v_mfma_f32_16x16x32_bf16 v[36:39], v[124:127], v[196:199], v[36:39]
	v_mfma_f32_16x16x32_bf16 v[40:43], v[176:179], v[196:199], v[40:43]
	v_mfma_f32_16x16x32_bf16 v[44:47], v[124:127], v[204:207], v[44:47]
	v_mfma_f32_16x16x32_bf16 v[188:191], v[124:127], v[212:215], v[48:51]
	v_mfma_f32_16x16x32_bf16 v[48:51], v[172:175], v[208:211], v[56:59]
	v_mfma_f32_16x16x32_bf16 v[192:195], v[176:179], v[212:215], v[48:51]
	s_barrier
	s_mov_b32 m0, s96
	v_lshl_add_u64 v[180:181], s[42:43], 0, v[130:131]
	s_add_u32 s18, s42, 0x10000
	s_nop 1
	ds_read_b128 v[48:51], v151 offset:16384
	ds_read_b128 v[52:55], v151 offset:17408
	ds_read_b128 v[56:59], v151 offset:18432
	ds_read_b128 v[88:91], v151 offset:19456
	ds_read_b128 v[92:95], v151 offset:20480
	ds_read_b128 v[196:199], v151 offset:21504
	ds_read_b128 v[200:203], v151 offset:22528
	ds_read_b128 v[204:207], v151 offset:23552
	global_load_lds_dwordx4 v[180:181], off
	v_lshl_add_u64 v[182:183], s[42:43], 0, v[134:135]
	s_mov_b32 m0, s29
	s_addc_u32 s19, s43, 0
	global_load_lds_dwordx4 v[182:183], off
	v_lshl_add_u64 v[208:209], s[18:19], 0, v[130:131]
	s_mov_b32 m0, s94
	v_lshl_add_u64 v[224:225], s[44:45], 0, v[128:129]
	global_load_lds_dwordx4 v[208:209], off
	v_lshl_add_u64 v[208:209], s[18:19], 0, v[134:135]
	s_mov_b32 m0, s95
	v_lshl_add_u64 v[138:139], s[44:45], 0, v[132:133]
	global_load_lds_dwordx4 v[208:209], off
	s_mov_b32 m0, s37
	s_nop 0
	global_load_lds_dwordx4 v[224:225], off
	s_mov_b32 m0, s47
	s_nop 0
	global_load_lds_dwordx4 v[138:139], off
	s_waitcnt vmcnt(8)
	s_waitcnt lgkmcnt(0)
	s_barrier
	s_waitcnt lgkmcnt(0)
	v_mfma_f32_16x16x32_bf16 v[0:3], v[104:107], v[200:203], v[0:3]
	v_mfma_f32_16x16x32_bf16 v[4:7], v[112:115], v[200:203], v[4:7]
	v_mfma_f32_16x16x32_bf16 v[142:145], v[104:107], v[48:51], v[142:145]
	v_mfma_f32_16x16x32_bf16 v[152:155], v[112:115], v[48:51], v[152:155]
	v_mfma_f32_16x16x32_bf16 v[156:159], v[104:107], v[56:59], v[156:159]
	v_mfma_f32_16x16x32_bf16 v[160:163], v[112:115], v[56:59], v[160:163]
	v_mfma_f32_16x16x32_bf16 v[164:167], v[104:107], v[92:95], v[164:167]
	v_mfma_f32_16x16x32_bf16 v[168:171], v[112:115], v[92:95], v[168:171]
	v_mfma_f32_16x16x32_bf16 v[0:3], v[108:111], v[204:207], v[0:3]
	v_mfma_f32_16x16x32_bf16 v[4:7], v[116:119], v[204:207], v[4:7]
	v_mfma_f32_16x16x32_bf16 v[142:145], v[108:111], v[52:55], v[142:145]
	v_mfma_f32_16x16x32_bf16 v[152:155], v[116:119], v[52:55], v[152:155]
	v_mfma_f32_16x16x32_bf16 v[156:159], v[108:111], v[88:91], v[156:159]
	v_mfma_f32_16x16x32_bf16 v[160:163], v[116:119], v[88:91], v[160:163]
	v_mfma_f32_16x16x32_bf16 v[164:167], v[108:111], v[196:199], v[164:167]
	v_mfma_f32_16x16x32_bf16 v[168:171], v[116:119], v[196:199], v[168:171]
	v_mfma_f32_16x16x32_bf16 v[24:27], v[120:123], v[56:59], v[24:27]
	v_mfma_f32_16x16x32_bf16 v[208:211], v[124:127], v[88:91], v[24:27]
	v_mfma_f32_16x16x32_bf16 v[24:27], v[172:175], v[56:59], v[28:31]
	v_mfma_f32_16x16x32_bf16 v[8:11], v[120:123], v[48:51], v[8:11]
	v_mfma_f32_16x16x32_bf16 v[12:15], v[172:175], v[48:51], v[12:15]
	v_mfma_f32_16x16x32_bf16 v[212:215], v[176:179], v[88:91], v[24:27]
	v_mfma_f32_16x16x32_bf16 v[24:27], v[120:123], v[92:95], v[60:63]
	v_mfma_f32_16x16x32_bf16 v[16:19], v[120:123], v[200:203], v[16:19]
	v_mfma_f32_16x16x32_bf16 v[8:11], v[124:127], v[52:55], v[8:11]
	v_mfma_f32_16x16x32_bf16 v[12:15], v[176:179], v[52:55], v[12:15]
	v_mfma_f32_16x16x32_bf16 v[226:229], v[124:127], v[196:199], v[24:27]
	v_mfma_f32_16x16x32_bf16 v[24:27], v[172:175], v[92:95], v[100:103]
	v_mfma_f32_16x16x32_bf16 v[230:233], v[124:127], v[204:207], v[16:19]
	v_mfma_f32_16x16x32_bf16 v[16:19], v[172:175], v[200:203], v[20:23]
	v_mfma_f32_16x16x32_bf16 v[196:199], v[176:179], v[196:199], v[24:27]
	v_mfma_f32_16x16x32_bf16 v[172:175], v[176:179], v[204:207], v[16:19]
	s_barrier
; #define PG8_STAGE(bufoff, gbase, voff) do { _Pragma("unroll") for (int _i = 0; _i < 2; ++_i) \
;         __builtin_amdgcn_global_load_lds((const unsigned*)((const char*)(gbase) + (voff)[_i]), (PG8_LAS unsigned*)(lds + (bufoff) + ldsw + _i * 8192), 16, 0, 0); } while (0)
; #define PG8_LDA(dst, b, h) do { _Pragma("unroll") for (int m = 0; m < 4; ++m) _Pragma("unroll") for (int k = 0; k < 2; ++k) dst[m][k] = *(const PG8_LAS bf16x8*)(lds + PG8_SA(b, h) + aoff + m * 2048 + k * 1024); } while (0)
; #define PG8_LDB(dst, b, h) do { _Pragma("unroll") for (int n = 0; n < 2; ++n) _Pragma("unroll") for (int k = 0; k < 2; ++k) dst[n][k] = *(const PG8_LAS bf16x8*)(lds + PG8_SB(b, h) + boff + n * 2048 + k * 1024); } while (0)
; #define PG8_MMA(ai, bj, At, Bt) do { __builtin_amdgcn_s_setprio(1); _Pragma("unroll") for (int m = 0; m < 4; ++m) _Pragma("unroll") for (int n = 0; n < 2; ++n) _Pragma("unroll") for (int k = 0; k < 2; ++k) \
;         acc[ai][bj][m][n] = __builtin_amdgcn_mfma_f32_16x16x32_bf16(Bt[n][k], At[m][k], acc[ai][bj][m][n], 0, 0, 0); __builtin_amdgcn_s_setprio(0); } while (0)
; #define PG8_WAIT_V(n) asm volatile("s_waitcnt vmcnt(" #n ")" ::: "memory")
; #define PG8_WAIT_L(n) asm volatile("s_waitcnt lgkmcnt(" #n ")" ::: "memory")
; #define PG8_BAR __builtin_amdgcn_s_barrier()
; #define PG8_SCHED __builtin_amdgcn_sched_barrier(0)
; template <class Epi>
; DI void gemm_phase(PG8_LAS unsigned char* lds, const Gemm g, const StaticOrder& S, const Epi& E) {
;     ...
;             PG8_LDB(B0, 1, 0); PG8_LDB(B1, 1, 1); PG8_SCHED; PG8_LDA(At, 1, 0); PG8_STAGE(PG8_SA(0, 1), a2 + hstepA, voffA);
;             PG8_WAIT_V(8); PG8_WAIT_L(0); PG8_BAR; PG8_MMA(0, 0, At, B0); PG8_MMA(0, 1, At, B1); PG8_BAR; PG8_SCHED;
;             PG8_LDA(At, 1, 1); PG8_STAGE(PG8_SB(1, 0), b3, voffB); PG8_STAGE(PG8_SB(1, 1), b3 + hstepB, voffB); PG8_STAGE(PG8_SA(1, 0), a3, voffA);
;             PG8_WAIT_V(8); PG8_WAIT_L(0); PG8_BAR; PG8_MMA(1, 0, At, B0); PG8_MMA(1, 1, At, B1); PG8_BAR; PG8_SCHED;
;         }
;         if (wr == 0) PG8_BAR;
	s_nop 3
	ds_read_b128 v[16:19], v136
	ds_read_b128 v[20:23], v136 offset:1024
	ds_read_b128 v[28:31], v136 offset:2048
	ds_read_b128 v[176:179], v136 offset:3072
	ds_read_b128 v[200:203], v238
	ds_read_b128 v[204:207], v238 offset:1024
	ds_read_b128 v[234:237], v238 offset:2048
	ds_read_b128 v[238:241], v238 offset:3072
	s_add_u32 s18, s44, 0x40000
	s_addc_u32 s19, s45, 0
	s_mov_b32 m0, s48
	v_lshl_add_u64 v[52:53], s[18:19], 0, v[128:129]
	ds_read_b128 v[24:27], v151 offset:32768
	ds_read_b128 v[48:51], v151 offset:33792
	ds_read_b128 v[100:103], v151 offset:34816
	ds_read_b128 v[112:115], v151 offset:35840
	ds_read_b128 v[116:119], v151 offset:36864
	ds_read_b128 v[242:245], v151 offset:37888
	ds_read_b128 v[246:249], v151 offset:38912
	ds_read_b128 v[250:253], v151 offset:39936
	global_load_lds_dwordx4 v[52:53], off
	v_lshl_add_u64 v[52:53], s[18:19], 0, v[132:133]
	s_mov_b32 m0, s49
	s_nop 0
	global_load_lds_dwordx4 v[52:53], off
	s_waitcnt vmcnt(8)
	s_waitcnt lgkmcnt(0)
	s_barrier
	s_waitcnt lgkmcnt(0)
	v_mfma_f32_16x16x32_bf16 v[52:55], v[16:19], v[24:27], v[64:67]
	v_mfma_f32_16x16x32_bf16 v[124:127], v[20:23], v[48:51], v[52:55]
	v_mfma_f32_16x16x32_bf16 v[52:55], v[28:31], v[24:27], v[68:71]
	v_mfma_f32_16x16x32_bf16 v[120:123], v[176:179], v[48:51], v[52:55]
	v_mfma_f32_16x16x32_bf16 v[52:55], v[16:19], v[100:103], v[72:75]
	v_mfma_f32_16x16x32_bf16 v[108:111], v[20:23], v[112:115], v[52:55]
	v_mfma_f32_16x16x32_bf16 v[52:55], v[28:31], v[100:103], v[76:79]
	v_mfma_f32_16x16x32_bf16 v[104:107], v[176:179], v[112:115], v[52:55]
	v_mfma_f32_16x16x32_bf16 v[52:55], v[16:19], v[116:119], v[80:83]
	v_mfma_f32_16x16x32_bf16 v[92:95], v[20:23], v[242:245], v[52:55]
	v_mfma_f32_16x16x32_bf16 v[52:55], v[28:31], v[116:119], v[84:87]
	v_mfma_f32_16x16x32_bf16 v[88:91], v[176:179], v[242:245], v[52:55]
	v_mfma_f32_16x16x32_bf16 v[52:55], v[16:19], v[246:249], v[216:219]
	v_mfma_f32_16x16x32_bf16 v[76:79], v[20:23], v[250:253], v[52:55]
	v_mfma_f32_16x16x32_bf16 v[52:55], v[28:31], v[246:249], v[220:223]
	v_mfma_f32_16x16x32_bf16 v[72:75], v[176:179], v[250:253], v[52:55]
	v_mfma_f32_16x16x32_bf16 v[52:55], v[200:203], v[24:27], v[96:99]
	v_mfma_f32_16x16x32_bf16 v[24:27], v[234:237], v[24:27], v[32:35]
	v_mfma_f32_16x16x32_bf16 v[56:59], v[238:241], v[48:51], v[24:27]
	v_mfma_f32_16x16x32_bf16 v[24:27], v[200:203], v[100:103], v[36:39]
	v_mfma_f32_16x16x32_bf16 v[60:63], v[204:207], v[48:51], v[52:55]
	v_mfma_f32_16x16x32_bf16 v[52:55], v[204:207], v[112:115], v[24:27]
	v_mfma_f32_16x16x32_bf16 v[24:27], v[234:237], v[100:103], v[40:43]
	v_mfma_f32_16x16x32_bf16 v[48:51], v[238:241], v[112:115], v[24:27]
	v_mfma_f32_16x16x32_bf16 v[24:27], v[200:203], v[116:119], v[44:47]
	v_mfma_f32_16x16x32_bf16 v[44:47], v[204:207], v[242:245], v[24:27]
	v_mfma_f32_16x16x32_bf16 v[24:27], v[234:237], v[116:119], v[184:187]
	v_mfma_f32_16x16x32_bf16 v[40:43], v[238:241], v[242:245], v[24:27]
	v_mfma_f32_16x16x32_bf16 v[24:27], v[200:203], v[246:249], v[188:191]
	v_mfma_f32_16x16x32_bf16 v[32:35], v[204:207], v[250:253], v[24:27]
	v_mfma_f32_16x16x32_bf16 v[24:27], v[234:237], v[246:249], v[192:195]
	v_mfma_f32_16x16x32_bf16 v[24:27], v[238:241], v[250:253], v[24:27]
	s_barrier
	s_mov_b32 m0, vcc_hi
	v_lshl_add_u64 v[36:37], v[180:181], 0, s[8:9]
	s_add_u32 s18, s42, 0x10080
	ds_read_b128 v[184:187], v151 offset:49152
	ds_read_b128 v[188:191], v151 offset:50176
	ds_read_b128 v[192:195], v151 offset:51200
	ds_read_b128 v[216:219], v151 offset:52224
	ds_read_b128 v[220:223], v151 offset:53248
	ds_read_b128 v[242:245], v151 offset:54272
	ds_read_b128 v[246:249], v151 offset:55296
	ds_read_b128 v[250:253], v151 offset:56320
	global_load_lds_dwordx4 v[36:37], off
	v_lshl_add_u64 v[36:37], v[182:183], 0, s[8:9]
	s_mov_b32 m0, s97
	s_addc_u32 s19, s43, 0
	global_load_lds_dwordx4 v[36:37], off
	v_lshl_add_u64 v[36:37], s[18:19], 0, v[130:131]
	s_mov_b32 m0, s40
	s_nop 0
	global_load_lds_dwordx4 v[36:37], off
	v_lshl_add_u64 v[36:37], s[18:19], 0, v[134:135]
	s_mov_b32 m0, s41
	s_nop 0
	global_load_lds_dwordx4 v[36:37], off
	v_lshl_add_u64 v[36:37], v[224:225], 0, s[8:9]
	s_mov_b32 m0, s53
	s_nop 0
	global_load_lds_dwordx4 v[36:37], off
	v_lshl_add_u64 v[36:37], v[138:139], 0, s[8:9]
	s_mov_b32 m0, s55
	s_nop 0
	global_load_lds_dwordx4 v[36:37], off
	s_waitcnt vmcnt(8)
	s_waitcnt lgkmcnt(0)
	s_barrier
	s_waitcnt lgkmcnt(0)
	v_mfma_f32_16x16x32_bf16 v[36:39], v[16:19], v[184:187], v[142:145]
	v_mfma_f32_16x16x32_bf16 v[116:119], v[20:23], v[188:191], v[36:39]
	v_mfma_f32_16x16x32_bf16 v[36:39], v[28:31], v[184:187], v[152:155]
	v_mfma_f32_16x16x32_bf16 v[112:115], v[176:179], v[188:191], v[36:39]
	v_mfma_f32_16x16x32_bf16 v[36:39], v[16:19], v[192:195], v[156:159]
	v_mfma_f32_16x16x32_bf16 v[100:103], v[20:23], v[216:219], v[36:39]
	v_mfma_f32_16x16x32_bf16 v[36:39], v[28:31], v[192:195], v[160:163]
	v_mfma_f32_16x16x32_bf16 v[96:99], v[176:179], v[216:219], v[36:39]
	v_mfma_f32_16x16x32_bf16 v[36:39], v[16:19], v[220:223], v[164:167]
	v_mfma_f32_16x16x32_bf16 v[0:3], v[16:19], v[246:249], v[0:3]
	v_mfma_f32_16x16x32_bf16 v[84:87], v[20:23], v[242:245], v[36:39]
	v_mfma_f32_16x16x32_bf16 v[36:39], v[28:31], v[220:223], v[168:171]
	v_mfma_f32_16x16x32_bf16 v[68:71], v[20:23], v[250:253], v[0:3]
	v_mfma_f32_16x16x32_bf16 v[0:3], v[28:31], v[246:249], v[4:7]
	v_mfma_f32_16x16x32_bf16 v[80:83], v[176:179], v[242:245], v[36:39]
	v_mfma_f32_16x16x32_bf16 v[64:67], v[176:179], v[250:253], v[0:3]
	v_mfma_f32_16x16x32_bf16 v[0:3], v[200:203], v[184:187], v[8:11]
	v_mfma_f32_16x16x32_bf16 v[36:39], v[204:207], v[188:191], v[0:3]
	v_mfma_f32_16x16x32_bf16 v[0:3], v[234:237], v[184:187], v[12:15]
	v_mfma_f32_16x16x32_bf16 v[28:31], v[238:241], v[188:191], v[0:3]
	v_mfma_f32_16x16x32_bf16 v[0:3], v[200:203], v[192:195], v[208:211]
	v_mfma_f32_16x16x32_bf16 v[20:23], v[204:207], v[216:219], v[0:3]
	v_mfma_f32_16x16x32_bf16 v[0:3], v[234:237], v[192:195], v[212:215]
	v_mfma_f32_16x16x32_bf16 v[16:19], v[238:241], v[216:219], v[0:3]
	v_mfma_f32_16x16x32_bf16 v[0:3], v[200:203], v[220:223], v[226:229]
	v_mfma_f32_16x16x32_bf16 v[12:15], v[204:207], v[242:245], v[0:3]
	v_mfma_f32_16x16x32_bf16 v[0:3], v[234:237], v[220:223], v[196:199]
	v_mfma_f32_16x16x32_bf16 v[8:11], v[238:241], v[242:245], v[0:3]
	v_mfma_f32_16x16x32_bf16 v[0:3], v[200:203], v[246:249], v[230:233]
	v_mfma_f32_16x16x32_bf16 v[4:7], v[204:207], v[250:253], v[0:3]
	v_mfma_f32_16x16x32_bf16 v[0:3], v[234:237], v[246:249], v[172:175]
	v_mfma_f32_16x16x32_bf16 v[0:3], v[238:241], v[250:253], v[0:3]
	s_barrier
	s_andn2_b64 vcc, exec, s[10:11]
	s_cbranch_vccnz .LBB0_468
	s_barrier
